# first-iteration peel (srcC=0 MFMAs, no accumulator zeroing copies) extended to the G3a main loop; on top of v75
# speedup vs baseline: 1.0080x; 1.0012x over previous
; #define PG8_STAGEX(rs, bufoff, soff, voff) do { _Pragma("unroll") for (int _i = 0; _i < 2; ++_i) \
;         __builtin_amdgcn_raw_ptr_buffer_load_lds(rs, (LAS unsigned*)(lds + (bufoff) + ldsw + _i * 8192), 16, (voff)[_i], (soff), 0, 0); } while (0)
; #define PG8_LDA(dst, b, h) do { _Pragma("unroll") for (int m = 0; m < 4; ++m) _Pragma("unroll") for (int k = 0; k < 2; ++k) dst[m][k] = *(const LAS bf16x8*)(lds + PG8_SA(b, h) + aoff + m * 2048 + k * 1024); } while (0)
; #define PG8_LDB(dst, b, h) do { _Pragma("unroll") for (int n = 0; n < 2; ++n) _Pragma("unroll") for (int k = 0; k < 2; ++k) dst[n][k] = *(const LAS bf16x8*)(lds + PG8_SB(b, h) + boff + n * 2048 + k * 1024); } while (0)
; #define PG8_WAIT_V(n) asm volatile("s_waitcnt vmcnt(" #n ")" ::: "memory")
; #define PG8_WAIT_L(n) asm volatile("s_waitcnt lgkmcnt(" #n ")" ::: "memory")
; #define PG8_BAR __builtin_amdgcn_s_barrier()
; #define PG8_SCHED __builtin_amdgcn_sched_barrier(0)
;     ...
;         for (int t = 0; t < nt; t += 2) {
;             const bool last = (t == nt - 2);
;             const unsigned a1 = cA + (unsigned)(t + 1) * kstep;
;             const unsigned a2 = last ? nA : cA + (unsigned)(t + 2) * kstep, b2 = last ? nB : cB + (unsigned)(t + 2) * kstep;
;             const unsigned a3 = a2 + kstep, b3 = b2 + kstep;
;             PG8_LDB(B0, 0, 0); PG8_LDB(B1, 0, 1); PG8_SCHED; PG8_LDA(At, 0, 0); PG8_STAGEX(rsA, PG8_SA(1, 1), a1 + hstepA, voffA);
;             PG8_WAIT_V(8); PG8_WAIT_L(0); PG8_BAR; PG8_MMA(0, 0, At, B0); PG8_MMA(0, 1, At, B1); PG8_BAR; PG8_SCHED;
;             PG8_LDA(At, 0, 1); PG8_STAGEX(rsB, PG8_SB(0, 0), b2, voffB); PG8_STAGEX(rsB, PG8_SB(0, 1), b2 + hstepB, voffB); PG8_STAGEX(rsA, PG8_SA(0, 0), a2, voffA);
;             PG8_WAIT_V(8); PG8_WAIT_L(0); PG8_BAR; PG8_MMA(1, 0, At, B0); PG8_MMA(1, 1, At, B1); PG8_BAR; PG8_SCHED;
.LBB0_436:
	s_lshl_b32 s26, s25, 20
	s_and_b64 s[30:31], s[48:49], exec
	s_cselect_b32 s2, s26, s7
	s_lshl_b32 s27, s24, 20
	s_and_b64 s[30:31], s[48:49], exec
	s_waitcnt vmcnt(15)
	s_cselect_b32 s5, s27, s28
	s_add_i32 s7, s7, 0x80080
	s_addk_i32 s28, 0x100
	s_mov_b32 s29, -2
	v_add_u32_e32 v142, 0x10000, v220
	v_add_u32_e32 v158, 0x14000, v220
	ds_read_b128 v[130:133], v142
	ds_read_b128 v[134:137], v142 offset:1024
	ds_read_b128 v[138:141], v142 offset:2048
	ds_read_b128 v[142:145], v142 offset:3072
	ds_read_b128 v[146:149], v158
	ds_read_b128 v[150:153], v158 offset:1024
	ds_read_b128 v[154:157], v158 offset:2048
	ds_read_b128 v[158:161], v158 offset:3072
	s_add_i32 s30, s7, 0xfff80080
	s_cmp_eq_u32 s29, 28
	s_cselect_b32 s50, s2, s30
	s_cselect_b32 s31, s5, s28
	s_or_b32 s30, s50, 0x80
	s_mov_b32 m0, s20
	ds_read_b128 v[162:165], v221
	ds_read_b128 v[170:173], v221 offset:1024
	ds_read_b128 v[182:185], v221 offset:2048
	ds_read_b128 v[186:189], v221 offset:3072
	ds_read_b128 v[190:193], v221 offset:4096
	ds_read_b128 v[194:197], v221 offset:5120
	ds_read_b128 v[198:201], v221 offset:6144
	ds_read_b128 v[202:205], v221 offset:7168
	buffer_load_dwordx4 v178, s[76:79], s7 offen lds
	s_mov_b32 m0, s22
	s_nop 0
	buffer_load_dwordx4 v210, s[76:79], s7 offen lds
	s_waitcnt vmcnt(8)
	s_waitcnt lgkmcnt(0)
	s_setprio 1
	s_barrier
	v_mfma_f32_16x16x32_bf16 v[126:129], v[130:133], v[162:165], 0
	v_mfma_f32_16x16x32_bf16 v[126:129], v[134:137], v[170:173], v[126:129]
	v_mfma_f32_16x16x32_bf16 v[110:113], v[142:145], v[170:173], 0
	v_mfma_f32_16x16x32_bf16 v[110:113], v[138:141], v[162:165], v[110:113]
	v_mfma_f32_16x16x32_bf16 v[102:105], v[138:141], v[182:185], 0
	v_mfma_f32_16x16x32_bf16 v[102:105], v[142:145], v[186:189], v[102:105]
	v_mfma_f32_16x16x32_bf16 v[118:121], v[134:137], v[186:189], 0
	v_mfma_f32_16x16x32_bf16 v[118:121], v[130:133], v[182:185], v[118:121]
	v_mfma_f32_16x16x32_bf16 v[114:117], v[130:133], v[190:193], 0
	v_mfma_f32_16x16x32_bf16 v[114:117], v[134:137], v[194:197], v[114:117]
	v_mfma_f32_16x16x32_bf16 v[98:101], v[142:145], v[194:197], 0
	v_mfma_f32_16x16x32_bf16 v[98:101], v[138:141], v[190:193], v[98:101]
	v_mfma_f32_16x16x32_bf16 v[106:109], v[138:141], v[198:201], 0
	v_mfma_f32_16x16x32_bf16 v[106:109], v[142:145], v[202:205], v[106:109]
	v_mfma_f32_16x16x32_bf16 v[122:125], v[134:137], v[202:205], 0
	v_mfma_f32_16x16x32_bf16 v[122:125], v[130:133], v[198:201], v[122:125]
	v_mfma_f32_16x16x32_bf16 v[62:65], v[146:149], v[162:165], 0
	v_mfma_f32_16x16x32_bf16 v[62:65], v[150:153], v[170:173], v[62:65]
	v_mfma_f32_16x16x32_bf16 v[46:49], v[158:161], v[170:173], 0
	v_mfma_f32_16x16x32_bf16 v[46:49], v[154:157], v[162:165], v[46:49]
	v_mfma_f32_16x16x32_bf16 v[38:41], v[154:157], v[182:185], 0
	v_mfma_f32_16x16x32_bf16 v[38:41], v[158:161], v[186:189], v[38:41]
	v_mfma_f32_16x16x32_bf16 v[54:57], v[150:153], v[186:189], 0
	v_mfma_f32_16x16x32_bf16 v[54:57], v[146:149], v[182:185], v[54:57]
	v_mfma_f32_16x16x32_bf16 v[50:53], v[146:149], v[190:193], 0
	v_mfma_f32_16x16x32_bf16 v[50:53], v[150:153], v[194:197], v[50:53]
	v_mfma_f32_16x16x32_bf16 v[34:37], v[158:161], v[194:197], 0
	v_mfma_f32_16x16x32_bf16 v[34:37], v[154:157], v[190:193], v[34:37]
	v_mfma_f32_16x16x32_bf16 v[42:45], v[154:157], v[198:201], 0
	v_mfma_f32_16x16x32_bf16 v[42:45], v[158:161], v[202:205], v[42:45]
	v_mfma_f32_16x16x32_bf16 v[58:61], v[150:153], v[202:205], 0
	v_mfma_f32_16x16x32_bf16 v[58:61], v[146:149], v[198:201], v[58:61]
	s_barrier
	s_setprio 0
	s_mov_b32 m0, s90
	s_mov_b32 s58, s78
	s_mov_b32 s59, s79
	ds_read_b128 v[162:165], v221 offset:16384
	ds_read_b128 v[170:173], v221 offset:17408
	ds_read_b128 v[182:185], v221 offset:18432
	ds_read_b128 v[186:189], v221 offset:19456
	ds_read_b128 v[190:193], v221 offset:20480
	ds_read_b128 v[194:197], v221 offset:21504
	ds_read_b128 v[198:201], v221 offset:22528
	ds_read_b128 v[202:205], v221 offset:23552
	buffer_load_dwordx4 v179, s[56:59], s31 offen lds
	s_mov_b32 m0, s91
	s_add_i32 s51, s31, 0x80000
	buffer_load_dwordx4 v211, s[56:59], s31 offen lds
	s_mov_b32 m0, s9
	s_nop 0
	buffer_load_dwordx4 v179, s[56:59], s51 offen lds
	s_mov_b32 m0, s10
	s_nop 0
	buffer_load_dwordx4 v211, s[56:59], s51 offen lds
	s_mov_b32 m0, s89
	s_nop 0
	buffer_load_dwordx4 v178, s[76:79], s50 offen lds
	s_mov_b32 m0, s11
	s_nop 0
	buffer_load_dwordx4 v210, s[76:79], s50 offen lds
	s_waitcnt vmcnt(8)
	s_waitcnt lgkmcnt(0)
	s_setprio 1
	s_barrier
	v_mfma_f32_16x16x32_bf16 v[94:97], v[130:133], v[162:165], 0
	v_mfma_f32_16x16x32_bf16 v[94:97], v[134:137], v[170:173], v[94:97]
	v_mfma_f32_16x16x32_bf16 v[78:81], v[142:145], v[170:173], 0
	v_mfma_f32_16x16x32_bf16 v[78:81], v[138:141], v[162:165], v[78:81]
	v_mfma_f32_16x16x32_bf16 v[70:73], v[138:141], v[182:185], 0
	v_mfma_f32_16x16x32_bf16 v[70:73], v[142:145], v[186:189], v[70:73]
	v_mfma_f32_16x16x32_bf16 v[86:89], v[134:137], v[186:189], 0
	v_mfma_f32_16x16x32_bf16 v[86:89], v[130:133], v[182:185], v[86:89]
	v_mfma_f32_16x16x32_bf16 v[82:85], v[130:133], v[190:193], 0
	v_mfma_f32_16x16x32_bf16 v[82:85], v[134:137], v[194:197], v[82:85]
	v_mfma_f32_16x16x32_bf16 v[66:69], v[142:145], v[194:197], 0
	v_mfma_f32_16x16x32_bf16 v[66:69], v[138:141], v[190:193], v[66:69]
	v_mfma_f32_16x16x32_bf16 v[74:77], v[138:141], v[198:201], 0
	v_mfma_f32_16x16x32_bf16 v[74:77], v[142:145], v[202:205], v[74:77]
	v_mfma_f32_16x16x32_bf16 v[90:93], v[134:137], v[202:205], 0
	v_mfma_f32_16x16x32_bf16 v[90:93], v[130:133], v[198:201], v[90:93]
	v_mfma_f32_16x16x32_bf16 v[30:33], v[146:149], v[162:165], 0
	v_mfma_f32_16x16x32_bf16 v[30:33], v[150:153], v[170:173], v[30:33]
	v_mfma_f32_16x16x32_bf16 v[14:17], v[158:161], v[170:173], 0
	v_mfma_f32_16x16x32_bf16 v[14:17], v[154:157], v[162:165], v[14:17]
	v_mfma_f32_16x16x32_bf16 v[10:13], v[154:157], v[182:185], 0
	v_mfma_f32_16x16x32_bf16 v[10:13], v[158:161], v[186:189], v[10:13]
	v_mfma_f32_16x16x32_bf16 v[22:25], v[150:153], v[186:189], 0
	v_mfma_f32_16x16x32_bf16 v[22:25], v[146:149], v[182:185], v[22:25]
	v_mfma_f32_16x16x32_bf16 v[18:21], v[146:149], v[190:193], 0
	v_mfma_f32_16x16x32_bf16 v[18:21], v[150:153], v[194:197], v[18:21]
	v_mfma_f32_16x16x32_bf16 v[2:5], v[158:161], v[194:197], 0
	v_mfma_f32_16x16x32_bf16 v[2:5], v[154:157], v[190:193], v[2:5]
	v_mfma_f32_16x16x32_bf16 v[6:9], v[154:157], v[198:201], 0
	v_mfma_f32_16x16x32_bf16 v[6:9], v[158:161], v[202:205], v[6:9]
	v_mfma_f32_16x16x32_bf16 v[26:29], v[150:153], v[202:205], 0
	v_mfma_f32_16x16x32_bf16 v[26:29], v[146:149], v[198:201], v[26:29]
	s_barrier
; #define PG8_STAGEX(rs, bufoff, soff, voff) do { _Pragma("unroll") for (int _i = 0; _i < 2; ++_i) \
;         __builtin_amdgcn_raw_ptr_buffer_load_lds(rs, (LAS unsigned*)(lds + (bufoff) + ldsw + _i * 8192), 16, (voff)[_i], (soff), 0, 0); } while (0)
; #define PG8_LDA(dst, b, h) do { _Pragma("unroll") for (int m = 0; m < 4; ++m) _Pragma("unroll") for (int k = 0; k < 2; ++k) dst[m][k] = *(const LAS bf16x8*)(lds + PG8_SA(b, h) + aoff + m * 2048 + k * 1024); } while (0)
; #define PG8_LDB(dst, b, h) do { _Pragma("unroll") for (int n = 0; n < 2; ++n) _Pragma("unroll") for (int k = 0; k < 2; ++k) dst[n][k] = *(const LAS bf16x8*)(lds + PG8_SB(b, h) + boff + n * 2048 + k * 1024); } while (0)
; #define PG8_WAIT_V(n) asm volatile("s_waitcnt vmcnt(" #n ")" ::: "memory")
; #define PG8_WAIT_L(n) asm volatile("s_waitcnt lgkmcnt(" #n ")" ::: "memory")
; #define PG8_BAR __builtin_amdgcn_s_barrier()
; #define PG8_SCHED __builtin_amdgcn_sched_barrier(0)
;     ...
;             PG8_LDB(B0, 1, 0); PG8_LDB(B1, 1, 1); PG8_SCHED; PG8_LDA(At, 1, 0); PG8_STAGEX(rsA, PG8_SA(0, 1), a2 + hstepA, voffA);
;             PG8_WAIT_V(8); PG8_WAIT_L(0); PG8_BAR; PG8_MMA(0, 0, At, B0); PG8_MMA(0, 1, At, B1); PG8_BAR; PG8_SCHED;
;             PG8_LDA(At, 1, 1); PG8_STAGEX(rsB, PG8_SB(1, 0), b3, voffB); PG8_STAGEX(rsB, PG8_SB(1, 1), b3 + hstepB, voffB); PG8_STAGEX(rsA, PG8_SA(1, 0), a3, voffA);
;             PG8_WAIT_V(8); PG8_WAIT_L(0); PG8_BAR; PG8_MMA(1, 0, At, B0); PG8_MMA(1, 1, At, B1); PG8_BAR; PG8_SCHED;
	s_setprio 0
	v_add_u32_e32 v142, 0x18000, v220
	v_add_u32_e32 v158, 0x1c000, v220
	ds_read_b128 v[130:133], v142
	ds_read_b128 v[134:137], v142 offset:1024
	ds_read_b128 v[138:141], v142 offset:2048
	ds_read_b128 v[142:145], v142 offset:3072
	ds_read_b128 v[146:149], v158
	ds_read_b128 v[150:153], v158 offset:1024
	ds_read_b128 v[154:157], v158 offset:2048
	ds_read_b128 v[158:161], v158 offset:3072
	s_add_i32 s50, s50, 0x80000
	s_mov_b32 m0, s74
	ds_read_b128 v[162:165], v221 offset:32768
	ds_read_b128 v[170:173], v221 offset:33792
	ds_read_b128 v[182:185], v221 offset:34816
	ds_read_b128 v[186:189], v221 offset:35840
	ds_read_b128 v[190:193], v221 offset:36864
	ds_read_b128 v[194:197], v221 offset:37888
	ds_read_b128 v[198:201], v221 offset:38912
	ds_read_b128 v[202:205], v221 offset:39936
	buffer_load_dwordx4 v178, s[76:79], s50 offen lds
	s_mov_b32 m0, s12
	s_nop 0
	buffer_load_dwordx4 v210, s[76:79], s50 offen lds
	s_waitcnt vmcnt(8)
	s_waitcnt lgkmcnt(0)
	s_setprio 1
	s_barrier
	v_mfma_f32_16x16x32_bf16 v[126:129], v[130:133], v[162:165], v[126:129]
	v_mfma_f32_16x16x32_bf16 v[126:129], v[134:137], v[170:173], v[126:129]
	v_mfma_f32_16x16x32_bf16 v[110:113], v[142:145], v[170:173], v[110:113]
	v_mfma_f32_16x16x32_bf16 v[110:113], v[138:141], v[162:165], v[110:113]
	v_mfma_f32_16x16x32_bf16 v[102:105], v[138:141], v[182:185], v[102:105]
	v_mfma_f32_16x16x32_bf16 v[102:105], v[142:145], v[186:189], v[102:105]
	v_mfma_f32_16x16x32_bf16 v[118:121], v[134:137], v[186:189], v[118:121]
	v_mfma_f32_16x16x32_bf16 v[118:121], v[130:133], v[182:185], v[118:121]
	v_mfma_f32_16x16x32_bf16 v[114:117], v[130:133], v[190:193], v[114:117]
	v_mfma_f32_16x16x32_bf16 v[114:117], v[134:137], v[194:197], v[114:117]
	v_mfma_f32_16x16x32_bf16 v[98:101], v[142:145], v[194:197], v[98:101]
	v_mfma_f32_16x16x32_bf16 v[98:101], v[138:141], v[190:193], v[98:101]
	v_mfma_f32_16x16x32_bf16 v[106:109], v[138:141], v[198:201], v[106:109]
	v_mfma_f32_16x16x32_bf16 v[106:109], v[142:145], v[202:205], v[106:109]
	v_mfma_f32_16x16x32_bf16 v[122:125], v[134:137], v[202:205], v[122:125]
	v_mfma_f32_16x16x32_bf16 v[122:125], v[130:133], v[198:201], v[122:125]
	v_mfma_f32_16x16x32_bf16 v[62:65], v[146:149], v[162:165], v[62:65]
	v_mfma_f32_16x16x32_bf16 v[62:65], v[150:153], v[170:173], v[62:65]
	v_mfma_f32_16x16x32_bf16 v[46:49], v[158:161], v[170:173], v[46:49]
	v_mfma_f32_16x16x32_bf16 v[46:49], v[154:157], v[162:165], v[46:49]
	v_mfma_f32_16x16x32_bf16 v[38:41], v[154:157], v[182:185], v[38:41]
	v_mfma_f32_16x16x32_bf16 v[38:41], v[158:161], v[186:189], v[38:41]
	v_mfma_f32_16x16x32_bf16 v[54:57], v[150:153], v[186:189], v[54:57]
	v_mfma_f32_16x16x32_bf16 v[54:57], v[146:149], v[182:185], v[54:57]
	v_mfma_f32_16x16x32_bf16 v[50:53], v[146:149], v[190:193], v[50:53]
	v_mfma_f32_16x16x32_bf16 v[50:53], v[150:153], v[194:197], v[50:53]
	v_mfma_f32_16x16x32_bf16 v[34:37], v[158:161], v[194:197], v[34:37]
	v_mfma_f32_16x16x32_bf16 v[34:37], v[154:157], v[190:193], v[34:37]
	v_mfma_f32_16x16x32_bf16 v[42:45], v[154:157], v[198:201], v[42:45]
	v_mfma_f32_16x16x32_bf16 v[42:45], v[158:161], v[202:205], v[42:45]
	v_mfma_f32_16x16x32_bf16 v[58:61], v[150:153], v[202:205], v[58:61]
	v_mfma_f32_16x16x32_bf16 v[58:61], v[146:149], v[198:201], v[58:61]
	s_barrier
	s_setprio 0
	s_mov_b32 m0, s13
	s_or_b32 s50, s31, 0x80
	ds_read_b128 v[162:165], v221 offset:49152
	ds_read_b128 v[170:173], v221 offset:50176
	ds_read_b128 v[182:185], v221 offset:51200
	ds_read_b128 v[186:189], v221 offset:52224
	ds_read_b128 v[190:193], v221 offset:53248
	ds_read_b128 v[194:197], v221 offset:54272
	ds_read_b128 v[198:201], v221 offset:55296
	ds_read_b128 v[202:205], v221 offset:56320
	buffer_load_dwordx4 v179, s[56:59], s50 offen lds
	s_mov_b32 m0, s14
	s_add_i32 s31, s31, 0x80080
	buffer_load_dwordx4 v211, s[56:59], s50 offen lds
	s_mov_b32 m0, s17
	s_nop 0
	buffer_load_dwordx4 v179, s[56:59], s31 offen lds
	s_mov_b32 m0, s18
	s_nop 0
	buffer_load_dwordx4 v211, s[56:59], s31 offen lds
	s_mov_b32 m0, s15
	s_nop 0
	buffer_load_dwordx4 v178, s[76:79], s30 offen lds
	s_mov_b32 m0, s16
	s_nop 0
	buffer_load_dwordx4 v210, s[76:79], s30 offen lds
	s_waitcnt vmcnt(8)
	s_waitcnt lgkmcnt(0)
	s_setprio 1
	s_barrier
	v_mfma_f32_16x16x32_bf16 v[94:97], v[130:133], v[162:165], v[94:97]
	v_mfma_f32_16x16x32_bf16 v[94:97], v[134:137], v[170:173], v[94:97]
	v_mfma_f32_16x16x32_bf16 v[78:81], v[142:145], v[170:173], v[78:81]
	v_mfma_f32_16x16x32_bf16 v[78:81], v[138:141], v[162:165], v[78:81]
	v_mfma_f32_16x16x32_bf16 v[70:73], v[138:141], v[182:185], v[70:73]
	v_mfma_f32_16x16x32_bf16 v[70:73], v[142:145], v[186:189], v[70:73]
	v_mfma_f32_16x16x32_bf16 v[86:89], v[134:137], v[186:189], v[86:89]
	v_mfma_f32_16x16x32_bf16 v[86:89], v[130:133], v[182:185], v[86:89]
	v_mfma_f32_16x16x32_bf16 v[82:85], v[130:133], v[190:193], v[82:85]
	v_mfma_f32_16x16x32_bf16 v[82:85], v[134:137], v[194:197], v[82:85]
	v_mfma_f32_16x16x32_bf16 v[66:69], v[142:145], v[194:197], v[66:69]
	v_mfma_f32_16x16x32_bf16 v[66:69], v[138:141], v[190:193], v[66:69]
	v_mfma_f32_16x16x32_bf16 v[74:77], v[138:141], v[198:201], v[74:77]
	v_mfma_f32_16x16x32_bf16 v[74:77], v[142:145], v[202:205], v[74:77]
	v_mfma_f32_16x16x32_bf16 v[90:93], v[134:137], v[202:205], v[90:93]
	v_mfma_f32_16x16x32_bf16 v[90:93], v[130:133], v[198:201], v[90:93]
	v_mfma_f32_16x16x32_bf16 v[30:33], v[146:149], v[162:165], v[30:33]
	v_mfma_f32_16x16x32_bf16 v[30:33], v[150:153], v[170:173], v[30:33]
	v_mfma_f32_16x16x32_bf16 v[14:17], v[158:161], v[170:173], v[14:17]
	v_mfma_f32_16x16x32_bf16 v[14:17], v[154:157], v[162:165], v[14:17]
	v_mfma_f32_16x16x32_bf16 v[10:13], v[154:157], v[182:185], v[10:13]
	v_mfma_f32_16x16x32_bf16 v[10:13], v[158:161], v[186:189], v[10:13]
	v_mfma_f32_16x16x32_bf16 v[22:25], v[150:153], v[186:189], v[22:25]
	v_mfma_f32_16x16x32_bf16 v[22:25], v[146:149], v[182:185], v[22:25]
	v_mfma_f32_16x16x32_bf16 v[18:21], v[146:149], v[190:193], v[18:21]
	v_mfma_f32_16x16x32_bf16 v[18:21], v[150:153], v[194:197], v[18:21]
	v_mfma_f32_16x16x32_bf16 v[2:5], v[158:161], v[194:197], v[2:5]
	v_mfma_f32_16x16x32_bf16 v[2:5], v[154:157], v[190:193], v[2:5]
	v_mfma_f32_16x16x32_bf16 v[6:9], v[154:157], v[198:201], v[6:9]
	v_mfma_f32_16x16x32_bf16 v[6:9], v[158:161], v[202:205], v[6:9]
	v_mfma_f32_16x16x32_bf16 v[26:29], v[150:153], v[202:205], v[26:29]
	v_mfma_f32_16x16x32_bf16 v[26:29], v[146:149], v[198:201], v[26:29]
	s_barrier
	s_setprio 0
	s_add_i32 s29, s29, 2
	s_addk_i32 s7, 0x100
	s_addk_i32 s28, 0x100
	.p2align	6
